# work-queue preference: four XCDs (0,2,4,6) start on the FoX queue (v104 had three)
# baseline (speedup 1.0000x reference)
; #define LAS __attribute__((address_space(3)))
;     LAS int* sitem = (LAS int*)(lds + ITEM_OFF);
;     constexpr int N_D = 256, N_B = 2048, N_A = 128, N_C = 128, N_ALL = N_D + N_B + N_A + N_C;
;     const int pref = ((__builtin_amdgcn_s_getreg((3 << 11) | 20) & 3u) != 0u) ? 1 : 0;
;     auto fetch = [&]() -> int {
;         auto q1 = [&](int i) -> int { return i < N_A + N_C ? N_D + N_B + i : N_D + (i - (N_A + N_C)); };
;         if (pref == 0) { int i = (int)atomicAdd(ctr, 1u); if (i < N_D) return i; i = (int)atomicAdd(ctr + 32, 1u); return i < N_ALL - N_D ? q1(i) : N_ALL; }
;         int i = (int)atomicAdd(ctr + 32, 1u); if (i < N_ALL - N_D) return q1(i); i = (int)atomicAdd(ctr, 1u); return i < N_D ? i : N_ALL; };
;     int nxt = 0;
;     if (threadIdx.x == 0) nxt = fetch();
.LBB0_112:
	v_readlane_b32 s0, v253, 49
	v_readlane_b32 s1, v253, 50
	s_lshl_b32 s0, s0, 1
	v_readlane_b32 s1, v253, 51
	s_add_i32 s0, s0, s1
	s_ashr_i32 s1, s0, 31
	v_readlane_b32 s20, v251, 1
	s_lshl_b64 s[0:1], s[0:1], 2
	v_readlane_b32 s22, v251, 3
	v_readlane_b32 s23, v251, 4
	s_add_u32 s0, s22, s0
	s_addc_u32 s1, s23, s1
	v_writelane_b32 v253, s0, 55
	v_mov_b32_e32 v180, 0
	v_readlane_b32 s21, v251, 2
	v_writelane_b32 v253, s1, 56
	s_getreg_b32 s0, hwreg(HW_REG_XCC_ID, 0, 4)
	s_lshr_b32 s0, 0x55, s0
	s_and_b32 s0, s0, 1
	s_cmp_eq_u32 s0, 0
	s_cselect_b64 s[0:1], -1, 0
	v_writelane_b32 v253, s0, 57
	v_readlane_b32 s24, v251, 5
	v_readlane_b32 s25, v251, 6
	v_writelane_b32 v253, s1, 58
	v_readlane_b32 s26, v251, 7
	v_readlane_b32 s27, v251, 8
	s_mov_b64 s[0:1], exec
	v_readlane_b32 s20, v251, 13
	v_readlane_b32 s21, v251, 14
	s_and_b64 s[20:21], s[0:1], s[20:21]
	s_mov_b64 exec, s[20:21]
	s_cbranch_execz .LBB0_131
	v_readlane_b32 s20, v253, 57
	v_readlane_b32 s21, v253, 58
	s_and_b64 vcc, exec, s[20:21]
	s_cbranch_vccz .LBB0_123
	s_mov_b64 s[22:23], exec
	v_mbcnt_lo_u32_b32 v0, s22, 0
	v_mbcnt_hi_u32_b32 v0, s23, v0
	v_cmp_eq_u32_e32 vcc, 0, v0
	s_and_saveexec_b64 s[20:21], vcc
	s_cbranch_execz .LBB0_116
	s_bcnt1_i32_b64 s22, s[22:23]
	v_mov_b32_e32 v2, s22
	v_readlane_b32 s22, v253, 55
	v_readlane_b32 s23, v253, 56
	s_nop 4
	global_atomic_add v2, v1, v2, s[22:23] offset:128 sc0
